# m3 norm-weight load hoisted out of the chunk loop into the preheader
# baseline (speedup 1.0000x reference)
.LBB0_446:
	s_or_b64 exec, exec, s[0:1]
	s_mov_b64 s[2:3], s[72:73]
	v_readlane_b32 s12, v254, 35
	v_readlane_b32 s0, v254, 60
	s_and_b64 vcc, exec, s[58:59]
	s_waitcnt lgkmcnt(0)
	s_barrier
	v_readlane_b32 s1, v254, 61
	s_cbranch_vccz .LBB0_494
	s_load_dwordx2 s[0:1], s[2:3], 0x88
	s_load_dwordx8 s[4:11], s[2:3], 0x48
	s_nop 0
	s_load_dwordx2 s[2:3], s[2:3], 0x68
	s_mov_b32 s39, s70
	s_waitcnt lgkmcnt(0)
	s_add_u32 s14, s0, 0xc000000
	s_addc_u32 s15, s1, 0
	s_add_u32 s33, s0, 0xe000000
	s_addc_u32 s36, s1, 0
	s_lshl_b32 s16, s12, 12
	s_ashr_i32 s17, s16, 31
	s_lshl_b64 s[16:17], s[16:17], 2
	s_add_u32 s16, s4, s16
	s_addc_u32 s17, s5, s17
	s_lshl_b32 s4, s12, 10
	s_ashr_i32 s5, s4, 31
	s_lshl_b64 s[4:5], s[4:5], 2
	s_add_u32 s18, s6, s4
	s_addc_u32 s19, s7, s5
	s_add_u32 s37, s0, 0x18200000
	s_addc_u32 s38, s1, 0
	s_lshl_b32 s4, s12, 7
	s_ashr_i32 s5, s4, 31
	s_lshl_b64 s[4:5], s[4:5], 2
	s_add_u32 s20, s2, s4
	s_addc_u32 s21, s3, s5
	s_add_u32 s22, s0, 0x12000000
	s_addc_u32 s23, s1, 0
	s_add_u32 s24, s0, 0x4000000
	s_addc_u32 s25, s1, 0
	s_lshl_b32 s2, s12, 3
	s_ashr_i32 s3, s2, 31
	s_lshl_b64 s[2:3], s[2:3], 2
	s_add_u32 s26, s10, s2
	s_addc_u32 s27, s11, s3
	s_add_u32 s28, s8, s2
	s_addc_u32 s29, s9, s3
	s_add_u32 s30, s0, 0x18000000
	s_addc_u32 s31, s1, 0
	v_lshlrev_b32_e32 v0, 4, v194
	global_load_dwordx4 v[4:7], v0, s[16:17]
	s_add_u32 s90, s16, 0x2000
	s_addc_u32 s91, s17, 0
	global_load_dwordx4 v[8:11], v0, s[90:91]
	v_cmp_gt_u32_e32 vcc, 0x100, v194
	s_and_saveexec_b64 s[92:93], vcc
	global_load_dwordx4 v[12:15], v0, s[18:19]
	s_mov_b64 exec, s[92:93]
	v_and_b32_e32 v232, 63, v194
	v_lshlrev_b32_e32 v233, 3, v232
	global_load_dwordx2 v[234:235], v233, s[20:21]
	v_add_u32_e32 v1, 0x1a000, v0
	s_waitcnt vmcnt(0)
	ds_write_b128 v1, v[4:7]
	ds_write_b128 v1, v[8:11] offset:8192
	s_and_saveexec_b64 s[92:93], vcc
	ds_write_b128 v1, v[12:15] offset:16384
	s_mov_b64 exec, s[92:93]
	s_waitcnt lgkmcnt(0)
	s_barrier
	s_branch .LBB0_449

.LBB0_449:
	s_ashr_i32 s2, s39, 10
	s_and_b32 s41, s39, 0x7f
	s_ashr_i32 s3, s2, 31
	v_mov_b32_e32 v23, v194
	s_lshl_b64 s[34:35], s[2:3], 13
	s_lshl_b32 s2, s41, 6
	s_bfe_u32 s42, s39, 0x30007
	v_readfirstlane_b32 s40, v23
	s_or_b32 s34, s34, s2
	v_lshrrev_b32_e32 v209, 3, v23
	v_and_b32_e32 v210, 7, v23
	v_lshlrev_b32_e32 v211, 4, v210
	v_lshl_or_b32 v190, v209, 15, v211
	v_lshlrev_b32_e32 v191, 4, v23
	v_lshl_or_b32 v192, v209, 11, v211
	v_add_u32_e32 v193, 0x1000, v192
	v_lshlrev_b32_e32 v208, 5, v210
	s_lshl_b32 s90, s42, 7
	s_or_b32 s90, s90, 0x400
	s_lshl_b64 s[52:53], s[34:35], 1
	s_add_u32 s52, s33, s52
	s_addc_u32 s53, s36, s53
	s_lshl_b32 s91, s90, 15
	s_add_u32 s52, s52, s91
	s_addc_u32 s53, s53, 0
	s_add_u32 s54, s52, 0x200000
	s_addc_u32 s55, s53, 0
	global_load_dwordx4 v[44:47], v190, s[52:53]
	global_load_dwordx4 v[48:51], v190, s[54:55]
	s_mul_i32 s92, s39, 0x4080
	s_mul_hi_i32 s93, s39, 0x4080
	s_add_u32 s92, s37, s92
	s_addc_u32 s93, s38, s93
	global_load_dwordx4 v[52:55], v191, s[92:93]
	s_add_u32 s94, s92, 0x2000
	s_addc_u32 s95, s93, 0
	global_load_dwordx4 v[56:59], v191, s[94:95]
	s_add_u32 s94, s92, 0x4000
	s_addc_u32 s95, s93, 0
	v_cmp_gt_u32_e32 vcc, 8, v23
	s_and_saveexec_b64 s[96:97], vcc
	global_load_dwordx4 v[60:63], v191, s[94:95]
	s_mov_b64 exec, s[96:97]
	s_sub_u32 s92, s34, 3
	s_subb_u32 s93, s35, 0
	s_lshl_b64 s[92:93], s[92:93], 11
	s_add_u32 s92, s14, s92
	s_addc_u32 s93, s15, s93
	s_lshl_b32 s91, s42, 7
	s_add_u32 s92, s92, s91
	s_addc_u32 s93, s93, 0
	s_cmp_lg_u32 s41, 0
	s_cselect_b64 s[54:55], -1, 0
	v_cmp_lt_u32_e32 vcc, 2, v209
	s_or_b64 s[46:47], s[54:55], vcc
	v_cmp_lt_u32_e32 vcc, 1, v209
	s_or_b64 s[48:49], s[54:55], vcc
	v_cmp_lt_u32_e32 vcc, 0, v209
	s_or_b64 s[50:51], s[54:55], vcc
	s_mov_b64 s[96:97], exec
	s_and_b64 exec, s[96:97], s[46:47]
	global_load_dwordx4 v[80:83], v192, s[92:93]
	global_load_dwordx4 v[128:131], v192, s[92:93] offset:1024
	s_and_b64 exec, s[96:97], s[48:49]
	global_load_dwordx4 v[92:95], v192, s[92:93] offset:2048
	global_load_dwordx4 v[140:143], v192, s[92:93] offset:3072
	s_and_b64 exec, s[96:97], s[50:51]
	global_load_dwordx4 v[104:107], v193, s[92:93]
	global_load_dwordx4 v[152:155], v193, s[92:93] offset:1024
	s_mov_b64 exec, s[96:97]
	global_load_dwordx4 v[116:119], v193, s[92:93] offset:2048
	global_load_dwordx4 v[178:181], v193, s[92:93] offset:3072
	s_lshr_b32 s90, s40, 6
	s_lshl_b32 s90, s90, 3
	s_add_u32 s90, s34, s90
	s_addc_u32 s91, s35, 0
	s_lshl_b64 s[90:91], s[90:91], 11
	s_add_u32 s90, s22, s90
	s_addc_u32 s91, s23, s91
	s_lshl_b32 s92, s42, 8
	v_and_b32_e32 v232, 63, v23
	v_lshl_or_b32 v232, v232, 2, s92
	global_load_dword v224, v232, s[90:91]
	global_load_dword v225, v232, s[90:91] offset:2048
	s_add_u32 s90, s90, 0x1000
	s_addc_u32 s91, s91, 0
	global_load_dword v226, v232, s[90:91]
	global_load_dword v227, v232, s[90:91] offset:2048
	s_add_u32 s90, s90, 0x1000
	s_addc_u32 s91, s91, 0
	global_load_dword v228, v232, s[90:91]
	global_load_dword v229, v232, s[90:91] offset:2048
	s_add_u32 s90, s90, 0x1000
	s_addc_u32 s91, s91, 0
	global_load_dword v230, v232, s[90:91]
	global_load_dword v231, v232, s[90:91] offset:2048
	s_cmp_gt_u32 s40, 63
	v_and_b32_e32 v22, 63, v23
	s_cbranch_scc1 .LBB0_451
	v_or_b32_e32 v0, s34, v22
	v_mov_b32_e32 v1, s35
	v_lshlrev_b64 v[0:1], 6, v[0:1]
	v_lshl_add_u64 v[0:1], s[30:31], 0, v[0:1]
	s_lshl_b32 s86, s42, 2
	v_lshl_add_u64 v[0:1], v[0:1], 0, s[86:87]
	v_mov_b32_e32 v3, s86
	global_load_dword v2, v[0:1], off offset:32
	global_load_dword v4, v3, s[26:27]
	s_nop 0
	global_load_dword v0, v[0:1], off
	s_nop 0
	global_load_dword v1, v3, s[28:29]
	s_lshl_b32 s98, s39, 4
	s_add_u32 s98, s0, s98
	s_addc_u32 s99, s1, 0
	v_mov_b32_e32 v41, 0x18100000
	global_load_dword v42, v41, s[98:99] offset:8
	s_mov_b32 s2, 0x3f317218
	s_waitcnt vmcnt(2)
	v_add_f32_e32 v2, v2, v4
	s_waitcnt vmcnt(0)
	v_add_f32_e32 v1, v0, v1
	v_min_f32_e32 v0, 0, v2
	v_mul_f32_e64 v2, |v2|, s79
	v_exp_f32_e32 v4, v2
	s_nop 0
	v_add_f32_e32 v5, 1.0, v4
	v_add_f32_e32 v2, -1.0, v5
	v_sub_f32_e32 v3, v2, v5
	v_add_f32_e32 v3, 1.0, v3
	v_sub_f32_e32 v2, v4, v2
	v_add_f32_e32 v6, v2, v3
	v_frexp_mant_f32_e32 v2, v5
	v_cmp_gt_f32_e32 vcc, s85, v2
	v_cvt_f64_f32_e32 v[2:3], v5
	v_frexp_exp_i32_f64_e32 v2, v[2:3]
	v_subbrev_co_u32_e32 v2, vcc, 0, v2, vcc
	v_sub_u32_e32 v3, 0, v2
	v_ldexp_f32 v5, v5, v3
	v_ldexp_f32 v3, v6, v3
	v_add_f32_e32 v6, -1.0, v5
	v_add_f32_e32 v7, 1.0, v6
	v_sub_f32_e32 v7, v5, v7
	v_add_f32_e32 v7, v3, v7
	v_add_f32_e32 v8, v6, v7
	v_sub_f32_e32 v6, v8, v6
	v_sub_f32_e32 v6, v7, v6
	v_add_f32_e32 v7, 1.0, v5
	v_add_f32_e32 v9, -1.0, v7
	v_sub_f32_e32 v5, v5, v9
	v_add_f32_e32 v3, v3, v5
	v_add_f32_e32 v5, v7, v3
	v_sub_f32_e32 v7, v5, v7
	v_sub_f32_e32 v3, v3, v7
	v_rcp_f32_e32 v7, v5
	v_cvt_f32_i32_e32 v2, v2
	v_mul_f32_e32 v9, v8, v7
	v_mul_f32_e32 v10, v5, v9
	v_fma_f32 v11, v9, v5, -v10
	v_fmac_f32_e32 v11, v9, v3
	v_add_f32_e32 v12, v10, v11
	v_sub_f32_e32 v13, v8, v12
	v_sub_f32_e32 v8, v8, v13
	v_sub_f32_e32 v10, v12, v10
	v_sub_f32_e32 v8, v8, v12
	v_add_f32_e32 v6, v6, v8
	v_sub_f32_e32 v8, v10, v11
	v_add_f32_e32 v6, v8, v6
	v_add_f32_e32 v8, v13, v6
	v_mul_f32_e32 v10, v7, v8
	v_mul_f32_e32 v11, v5, v10
	v_fma_f32 v5, v10, v5, -v11
	v_fmac_f32_e32 v5, v10, v3
	v_sub_f32_e32 v3, v13, v8
	v_add_f32_e32 v3, v6, v3
	v_add_f32_e32 v6, v11, v5
	v_sub_f32_e32 v12, v8, v6
	v_sub_f32_e32 v8, v8, v12
	v_sub_f32_e32 v11, v6, v11
	v_sub_f32_e32 v6, v8, v6
	v_add_f32_e32 v3, v3, v6
	v_sub_f32_e32 v5, v11, v5
	v_add_f32_e32 v3, v5, v3
	v_add_f32_e32 v5, v9, v10
	v_add_f32_e32 v3, v12, v3
	v_sub_f32_e32 v6, v5, v9
	v_mul_f32_e32 v3, v7, v3
	v_sub_f32_e32 v6, v10, v6
	v_add_f32_e32 v3, v6, v3
	v_mul_f32_e32 v9, 0x3f317218, v2
	v_add_f32_e32 v6, v5, v3
	v_fma_f32 v10, v2, s2, -v9
	v_mul_f32_e32 v7, v6, v6
	v_fmac_f32_e32 v10, 0xb102e308, v2
	v_sub_f32_e32 v2, v6, v5
	v_fmamk_f32 v8, v7, 0x3e9b6dac, v200
	v_sub_f32_e32 v2, v3, v2
	v_add_f32_e32 v3, v9, v10
	v_fmaak_f32 v8, v7, v8, 0x3f2aaada
	v_sub_f32_e32 v5, v3, v9
	v_ldexp_f32 v9, v6, 1
	v_mul_f32_e32 v6, v6, v7
	v_mul_f32_e32 v6, v6, v8
	v_add_f32_e32 v7, v9, v6
	v_sub_f32_e32 v8, v7, v9
	v_ldexp_f32 v2, v2, 1
	v_sub_f32_e32 v6, v6, v8
	v_add_f32_e32 v2, v2, v6
	v_add_f32_e32 v6, v7, v2
	v_sub_f32_e32 v7, v6, v7
	v_sub_f32_e32 v2, v2, v7
	v_add_f32_e32 v7, v3, v6
	v_sub_f32_e32 v8, v7, v3
	v_sub_f32_e32 v9, v7, v8
	v_sub_f32_e32 v5, v10, v5
	v_sub_f32_e32 v3, v3, v9
	v_sub_f32_e32 v6, v6, v8
	v_add_f32_e32 v3, v6, v3
	v_add_f32_e32 v6, v5, v2
	v_sub_f32_e32 v8, v6, v5
	v_sub_f32_e32 v9, v6, v8
	v_sub_f32_e32 v5, v5, v9
	v_sub_f32_e32 v2, v2, v8
	v_add_f32_e32 v3, v6, v3
	v_add_f32_e32 v2, v2, v5
	v_add_f32_e32 v5, v7, v3
	v_sub_f32_e32 v6, v5, v7
	v_sub_f32_e32 v3, v3, v6
	v_add_f32_e32 v2, v2, v3
	s_mov_b32 s2, 0x7f800000
	v_add_f32_e32 v2, v5, v2
	v_cmp_neq_f32_e32 vcc, s2, v4
	s_mov_b32 s2, 0x33800000
	v_add_u32_e32 v3, -1, v201
	v_cndmask_b32_e32 v2, v202, v2, vcc
	v_cmp_ngt_f32_e32 vcc, -1.0, v4
	s_nop 1
	v_cndmask_b32_e32 v2, v203, v2, vcc
	v_cmp_neq_f32_e32 vcc, -1.0, v4
	s_nop 1
	v_cndmask_b32_e32 v2, v204, v2, vcc
	v_cmp_lt_f32_e64 vcc, |v4|, s2
	s_lshl_b32 s2, s39, 2
	s_ashr_i32 s3, s2, 31
	v_cndmask_b32_e32 v2, v2, v4, vcc
	v_sub_f32_e32 v0, v0, v2
	v_mov_b32_e32 v4, v0
	s_nop 1
	v_add_f32_dpp v4, v0, v4 row_shr:1 row_mask:0xf bank_mask:0xf
	v_add_f32_dpp v4, v0, v4 row_shr:2 row_mask:0xf bank_mask:0xf
	v_add_f32_dpp v4, v0, v4 row_shr:3 row_mask:0xf bank_mask:0xf
	s_nop 1
	v_add_f32_dpp v4, v4, v4 row_shr:4 row_mask:0xf bank_mask:0xe
	s_nop 1
	v_add_f32_dpp v4, v4, v4 row_shr:8 row_mask:0xf bank_mask:0xc
	s_nop 1
	v_add_f32_dpp v4, v4, v4 row_bcast:15 row_mask:0xa bank_mask:0xf
	s_nop 1
	v_add_f32_dpp v4, v4, v4 row_bcast:31 row_mask:0xc bank_mask:0xf
	v_mov_b32_e32 v0, v4
	v_sub_f32_e32 v1, v1, v0
	v_mov_b32_e32 v3, v1
	s_nop 1
	v_max_f32_dpp v3, v1, v3 row_shr:1 row_mask:0xf bank_mask:0xf
	v_max_f32_dpp v3, v1, v3 row_shr:2 row_mask:0xf bank_mask:0xf
	v_max_f32_dpp v3, v1, v3 row_shr:3 row_mask:0xf bank_mask:0xf
	s_nop 1
	v_max_f32_dpp v3, v3, v3 row_shr:4 row_mask:0xf bank_mask:0xe
	s_nop 1
	v_max_f32_dpp v3, v3, v3 row_shr:8 row_mask:0xf bank_mask:0xc
	s_nop 1
	v_max_f32_dpp v3, v3, v3 row_bcast:15 row_mask:0xa bank_mask:0xf
	s_nop 1
	v_max_f32_dpp v3, v3, v3 row_bcast:31 row_mask:0xc bank_mask:0xf
	v_mov_b32_e32 v2, v3
	v_max_f32_e32 v2, v2, v2
	s_waitcnt vmcnt(0)
	v_mov_b32_e32 v3, v42
	v_max_f32_e32 v4, v3, v3
	v_max_f32_e32 v2, v4, v2
	v_lshl_add_u32 v4, v22, 2, 0
	v_add_u32_e32 v4, 0x19200, v4
	ds_write2st64_b32 v4, v1, v2 offset1:1
	v_sub_f32_e32 v1, v3, v2
	v_add_f32_e32 v0, v0, v2
	v_mul_f32_e32 v1, 0x3fb8aa3b, v1
	v_mul_f32_e32 v0, 0xbfb8aa3b, v0
	v_exp_f32_e32 v1, v1
	v_exp_f32_e32 v0, v0
	ds_write2st64_b32 v4, v1, v0 offset0:2 offset1:3
